# v101 with the grid-barrier waiters polling back to back (s_sleep 0)
# baseline (speedup 1.0000x reference)
; __device__ __forceinline__ unsigned xb_ld(unsigned* p)              { return __hip_atomic_load(p, __ATOMIC_RELAXED, __HIP_MEMORY_SCOPE_AGENT); }
; __device__ __forceinline__ unsigned xb_add(unsigned* p, unsigned v) { return __hip_atomic_fetch_add(p, v, __ATOMIC_RELAXED, __HIP_MEMORY_SCOPE_AGENT); }
; #define XB_SPIN(cond, bar) do { unsigned _sp = 0; while (cond) { __builtin_amdgcn_s_sleep(6); \
;     if ((++_sp & 255u) == 0u) { if (xb_ld(&(bar)[XB_TMO])) break; if (_sp > XB_SPIN_CAP) { atomicAdd(&(bar)[XB_TMO], 1u); break; } } } } while (0)
; __device__ __forceinline__ void xcd_barrier(const XcdBarrier& b) {
;     ...
;             else XB_SPIN(xb_ld(&bar[XB_TOPGEN]) == tg, bar);
;             __builtin_amdgcn_fence(__ATOMIC_ACQUIRE, "agent");
;             xb_add(&bar[XB_XGEN(b.x)], 1u);
;             asm volatile("s_waitcnt vmcnt(0)" ::: "memory");
;         } else {
;             XB_SPIN(xb_ld(&bar[XB_XGEN(b.x)]) == gen, bar);
.LBB0_304:
	s_and_b32 s3, s2, 0xff
	s_mov_b64 s[16:17], -1
	s_cmp_lg_u32 s3, 0
	s_mov_b64 s[20:21], -1
	s_sleep 0
	s_cbranch_scc0 .LBB0_307
	s_and_b64 vcc, exec, s[20:21]
	s_cbranch_vccz .LBB0_303

; __device__ __forceinline__ unsigned xb_ld(unsigned* p)              { return __hip_atomic_load(p, __ATOMIC_RELAXED, __HIP_MEMORY_SCOPE_AGENT); }
; __device__ __forceinline__ unsigned xb_add(unsigned* p, unsigned v) { return __hip_atomic_fetch_add(p, v, __ATOMIC_RELAXED, __HIP_MEMORY_SCOPE_AGENT); }
; #define XB_SPIN(cond, bar) do { unsigned _sp = 0; while (cond) { __builtin_amdgcn_s_sleep(6); \
;     if ((++_sp & 255u) == 0u) { if (xb_ld(&(bar)[XB_TMO])) break; if (_sp > XB_SPIN_CAP) { atomicAdd(&(bar)[XB_TMO], 1u); break; } } } } while (0)
; __device__ __forceinline__ void xcd_barrier(const XcdBarrier& b) {
;     ...
;             else XB_SPIN(xb_ld(&bar[XB_TOPGEN]) == tg, bar);
;             __builtin_amdgcn_fence(__ATOMIC_ACQUIRE, "agent");
;             xb_add(&bar[XB_XGEN(b.x)], 1u);
;             asm volatile("s_waitcnt vmcnt(0)" ::: "memory");
;         } else {
;             XB_SPIN(xb_ld(&bar[XB_XGEN(b.x)]) == gen, bar);
.LBB0_321:
	s_and_b32 s3, s2, 0xff
	s_cmp_lg_u32 s3, 0
	s_mov_b64 s[20:21], -1
	s_sleep 0
	s_cbranch_scc0 .LBB0_324
	s_mov_b64 s[22:23], -1
	s_and_b64 vcc, exec, s[20:21]
	s_cbranch_vccz .LBB0_320

; __device__ __forceinline__ unsigned xb_ld(unsigned* p)              { return __hip_atomic_load(p, __ATOMIC_RELAXED, __HIP_MEMORY_SCOPE_AGENT); }
; __device__ __forceinline__ unsigned xb_add(unsigned* p, unsigned v) { return __hip_atomic_fetch_add(p, v, __ATOMIC_RELAXED, __HIP_MEMORY_SCOPE_AGENT); }
; #define XB_SPIN(cond, bar) do { unsigned _sp = 0; while (cond) { __builtin_amdgcn_s_sleep(6); \
;     if ((++_sp & 255u) == 0u) { if (xb_ld(&(bar)[XB_TMO])) break; if (_sp > XB_SPIN_CAP) { atomicAdd(&(bar)[XB_TMO], 1u); break; } } } } while (0)
; __device__ __forceinline__ void xcd_barrier(const XcdBarrier& b) {
;     ...
;             else XB_SPIN(xb_ld(&bar[XB_TOPGEN]) == tg, bar);
;             __builtin_amdgcn_fence(__ATOMIC_ACQUIRE, "agent");
;             xb_add(&bar[XB_XGEN(b.x)], 1u);
;             asm volatile("s_waitcnt vmcnt(0)" ::: "memory");
;         } else {
;             XB_SPIN(xb_ld(&bar[XB_XGEN(b.x)]) == gen, bar);
.LBB0_705:
	s_and_b32 s16, s3, 0xff
	s_mov_b64 s[14:15], -1
	s_cmp_lg_u32 s16, 0
	s_mov_b64 s[18:19], -1
	s_sleep 0
	s_cbranch_scc0 .LBB0_708
	s_and_b64 vcc, exec, s[18:19]
	s_cbranch_vccz .LBB0_704

; __device__ __forceinline__ unsigned xb_ld(unsigned* p)              { return __hip_atomic_load(p, __ATOMIC_RELAXED, __HIP_MEMORY_SCOPE_AGENT); }
; __device__ __forceinline__ unsigned xb_add(unsigned* p, unsigned v) { return __hip_atomic_fetch_add(p, v, __ATOMIC_RELAXED, __HIP_MEMORY_SCOPE_AGENT); }
; #define XB_SPIN(cond, bar) do { unsigned _sp = 0; while (cond) { __builtin_amdgcn_s_sleep(6); \
;     if ((++_sp & 255u) == 0u) { if (xb_ld(&(bar)[XB_TMO])) break; if (_sp > XB_SPIN_CAP) { atomicAdd(&(bar)[XB_TMO], 1u); break; } } } } while (0)
; __device__ __forceinline__ void xcd_barrier(const XcdBarrier& b) {
;     ...
;             else XB_SPIN(xb_ld(&bar[XB_TOPGEN]) == tg, bar);
;             __builtin_amdgcn_fence(__ATOMIC_ACQUIRE, "agent");
;             xb_add(&bar[XB_XGEN(b.x)], 1u);
;             asm volatile("s_waitcnt vmcnt(0)" ::: "memory");
;         } else {
;             XB_SPIN(xb_ld(&bar[XB_XGEN(b.x)]) == gen, bar);
.LBB0_1073:
	s_and_b32 s3, s2, 0xff
	s_mov_b64 s[18:19], -1
	s_cmp_lg_u32 s3, 0
	s_mov_b64 s[22:23], -1
	s_sleep 0
	s_cbranch_scc0 .LBB0_1076
	s_and_b64 vcc, exec, s[22:23]
	s_cbranch_vccz .LBB0_1072

; __device__ __forceinline__ unsigned xb_ld(unsigned* p)              { return __hip_atomic_load(p, __ATOMIC_RELAXED, __HIP_MEMORY_SCOPE_AGENT); }
; __device__ __forceinline__ unsigned xb_add(unsigned* p, unsigned v) { return __hip_atomic_fetch_add(p, v, __ATOMIC_RELAXED, __HIP_MEMORY_SCOPE_AGENT); }
; #define XB_SPIN(cond, bar) do { unsigned _sp = 0; while (cond) { __builtin_amdgcn_s_sleep(6); \
;     if ((++_sp & 255u) == 0u) { if (xb_ld(&(bar)[XB_TMO])) break; if (_sp > XB_SPIN_CAP) { atomicAdd(&(bar)[XB_TMO], 1u); break; } } } } while (0)
; __device__ __forceinline__ void xcd_barrier(const XcdBarrier& b) {
;     ...
;             else XB_SPIN(xb_ld(&bar[XB_TOPGEN]) == tg, bar);
;             __builtin_amdgcn_fence(__ATOMIC_ACQUIRE, "agent");
;             xb_add(&bar[XB_XGEN(b.x)], 1u);
;             asm volatile("s_waitcnt vmcnt(0)" ::: "memory");
;         } else {
;             XB_SPIN(xb_ld(&bar[XB_XGEN(b.x)]) == gen, bar);
.LBB0_1090:
	s_and_b32 s3, s2, 0xff
	s_cmp_lg_u32 s3, 0
	s_mov_b64 s[22:23], -1
	s_sleep 0
	s_cbranch_scc0 .LBB0_1093
	s_mov_b64 s[24:25], -1
	s_and_b64 vcc, exec, s[22:23]
	s_cbranch_vccz .LBB0_1089
